# speedup vs baseline: 1.0208x; 1.0208x over previous
; #define LAS __attribute__((address_space(3)))
; __device__ __forceinline__ unsigned cvt_pk_bf16(float lo, float hi) { return __builtin_bit_cast(unsigned, __builtin_amdgcn_cvt_pkrtz(lo, hi)); }
; #define bx (opaque_bx())
; #define ws (opaque_base(a.ws))
; __device__ __forceinline__ PrepTask prep_decode(const Args& a, int t) {
;     PrepTask T; const int l = t / PT_LAYER; int r = t % PT_LAYER; int nt;
;     if (r < PT_IN) { T.src = a.w_in + (size_t)l * DM * NIN; T.dst = (bf16_t*)(a.ws + WS_WIN + l * SZ_WIN); T.K = DM; T.Nnat = NIN; T.kind = KIND_IN; nt = 10; }
;     else if ((r -= PT_IN) < PT_OUT) { T.src = a.w_out + (size_t)l * DM * DM; T.dst = (bf16_t*)(a.ws + WS_WOUT + l * SZ_WOUT); T.K = DM; T.Nnat = DM; T.kind = KIND_STD; nt = 8; }
;     else if ((r -= PT_OUT) < PT_UP) { T.src = a.w_up + (size_t)l * DM * NUP; T.dst = (bf16_t*)(a.ws + WS_WUP + l * SZ_WUP); T.K = DM; T.Nnat = NUP; T.kind = KIND_UP; nt = 43; }
;     else if ((r -= PT_UP) < PT_DN) { T.src = a.w_down + (size_t)l * DFF * DM; T.dst = (bf16_t*)(a.ws + WS_WDN + l * SZ_WDN); T.K = DFF; T.Nnat = DM; T.kind = KIND_STD; nt = 8; }
;     else { r -= PT_DN; T.src = a.glu_w + (size_t)l * 512 * 1024; T.dst = (bf16_t*)(a.ws + WS_WGLU + l * SZ_WGLU); T.K = 512; T.Nnat = 1024; T.kind = KIND_GLU; nt = 4; }
;     (void)nt; const int KT = T.K / 64; T.pn = r / KT; T.k0 = (r % KT) * 64; return T;
; __device__ __forceinline__ void phase_prep(int wid_s, const Args& a, unsigned char* shm) {
;     ...
;         while (t < PT_TOTAL) {
;             { const int w = tid >> 6, s4 = tid & 63;
; #pragma unroll
;               for (int q = 0; q < 4; ++q) { const u32x4 pc = {cvt_pk_bf16(r[0][q], r[1][q]), cvt_pk_bf16(r[2][q], r[3][q]), cvt_pk_bf16(r[4][q], r[5][q]), cvt_pk_bf16(r[6][q], r[7][q])};
;                   *(LAS u32x4*)(Lp + (4 * s4 + q) * 36 + 4 * w) = pc; } }
;             __syncthreads();
;             const PrepTask C = T; ++j; const int tn = ((j >> 2) * G + bx) * 4 + (j & 3);
;             if (tn < PT_TOTAL) { T = prep_decode(a, tn); prep_load(T, r, tid); }
.LBB0_42:
	s_lshr_b32 s9, s37, 2
	s_mul_i32 s9, s9, s76
	v_readlane_b32 s12, v253, 0
	s_add_i32 s9, s9, s12
	s_cmpk_lt_u32 s9, 0x29c
	s_cbranch_scc1 .Lrm_done
	s_sub_u32 s98, s9, 0x29c
	s_movk_i32 s99, 0x29c
	s_cmpk_lt_u32 s98, 0x1fc
	s_cbranch_scc1 .Lrm_q
	s_sub_u32 s98, s98, 0x1fc
	s_addk_i32 s99, 0x29c
	s_cmpk_lt_u32 s98, 0x1fc
	s_cbranch_scc1 .Lrm_q
	s_sub_u32 s98, s98, 0x1fc
	s_addk_i32 s99, 0x29c
	s_cmpk_lt_u32 s98, 0x1fc
	s_cbranch_scc1 .Lrm_q
	s_sub_u32 s98, s98, 0x1fc
	s_addk_i32 s99, 0x29c
.Lrm_q:
	s_cmpk_lt_u32 s98, 0x90
	s_cbranch_scc1 .Lrm_add
	s_cmpk_lt_u32 s98, 0x130
	s_cbranch_scc1 .Lrm_odd
	s_addk_i32 s98, 0xa0
	s_branch .Lrm_add
.Lrm_odd:
	s_lshl_b32 s98, s98, 1
	s_sub_u32 s98, s98, 0x8f
.Lrm_add:
	s_add_u32 s9, s99, s98
.Lrm_done:
	s_lshl_b32 s9, s9, 2
	s_and_b32 s12, s37, 3
	s_waitcnt vmcnt(6)
	v_cvt_pkrtz_f16_f32 v54, v2, v6
	s_waitcnt vmcnt(4)
	v_cvt_pkrtz_f16_f32 v55, v10, v14
	s_waitcnt vmcnt(2)
	v_cvt_pkrtz_f16_f32 v56, v18, v22
	s_waitcnt vmcnt(0)
	v_cvt_pkrtz_f16_f32 v57, v26, v30
	s_or_b32 s9, s9, s12
	ds_write_b128 v52, v[54:57]
	v_cvt_pkrtz_f16_f32 v54, v3, v7
	v_cvt_pkrtz_f16_f32 v55, v11, v15
	v_cvt_pkrtz_f16_f32 v56, v19, v23
	v_cvt_pkrtz_f16_f32 v57, v27, v31
	v_readlane_b32 s13, v253, 1
	s_cmpk_gt_i32 s9, 0x29bf
	ds_write_b128 v52, v[54:57] offset:144
	v_cvt_pkrtz_f16_f32 v54, v4, v8
	v_cvt_pkrtz_f16_f32 v55, v12, v16
	v_cvt_pkrtz_f16_f32 v56, v20, v24
	v_cvt_pkrtz_f16_f32 v57, v28, v32
	s_cselect_b64 s[12:13], -1, 0
	ds_write_b128 v52, v[54:57] offset:288
	v_cvt_pkrtz_f16_f32 v54, v5, v9
	v_cvt_pkrtz_f16_f32 v55, v13, v17
	v_cvt_pkrtz_f16_f32 v56, v21, v25
	v_cvt_pkrtz_f16_f32 v57, v29, v33
	s_and_b64 vcc, exec, s[12:13]
	s_mov_b32 s18, s8
	ds_write_b128 v52, v[54:57] offset:432
	s_waitcnt lgkmcnt(0)
	s_barrier
	s_cbranch_vccnz .LBB0_41
	s_mul_hi_i32 s10, s9, 0x621b97c3
	s_lshr_b32 s11, s10, 31
	s_ashr_i32 s10, s10, 10
	s_add_i32 s20, s10, s11
	s_mul_i32 s10, s20, 0xa70
	s_sub_i32 s39, s9, s10
	s_cmpk_lt_i32 s39, 0x140
	s_cselect_b64 s[18:19], -1, 0
	s_cmpk_gt_i32 s39, 0x13f
	s_mov_b64 s[24:25], -1
	s_cbranch_scc0 .LBB0_55
	s_ashr_i32 s21, s20, 31
	s_cmpk_gt_u32 s39, 0x23f
	s_cbranch_scc0 .LBB0_52
	s_cmpk_gt_u32 s39, 0x79f
	s_mov_b64 s[22:23], -1
	s_cbranch_scc0 .LBB0_50
	s_cmpk_gt_u32 s39, 0xa4f
	s_mov_b64 s[16:17], -1
	s_cbranch_scc0 .LBB0_48
	v_readlane_b32 s40, v253, 5
	s_add_i32 s9, s39, 0xfffff5b0
	s_lshl_b64 s[10:11], s[20:21], 21
	v_readlane_b32 s50, v253, 15
	v_readlane_b32 s51, v253, 16
	s_add_u32 s14, s50, s10
	s_addc_u32 s15, s51, s11
	s_lshl_b64 s[10:11], s[20:21], 20
	s_add_u32 s10, s26, s10
	v_readlane_b32 s41, v253, 6
	v_readlane_b32 s42, v253, 7
	v_readlane_b32 s43, v253, 8
	v_readlane_b32 s44, v253, 9
	v_readlane_b32 s45, v253, 10
	v_readlane_b32 s46, v253, 11
	v_readlane_b32 s47, v253, 12
	v_readlane_b32 s48, v253, 13
	v_readlane_b32 s49, v253, 14
	v_readlane_b32 s52, v253, 17
	v_readlane_b32 s53, v253, 18
	v_readlane_b32 s54, v253, 19
	v_readlane_b32 s55, v253, 20
	s_addc_u32 s11, s27, s11
	s_mov_b64 s[16:17], 0

; __device__ __forceinline__ u32x2 pack4(f32x4 v) { u32x2 r; r.x = cvt_pk_bf16(v[0], v[1]); r.y = cvt_pk_bf16(v[2], v[3]); return r; }
; #define bx (opaque_bx())
; #define ws (opaque_base(a.ws))
; __device__ __forceinline__ void phase_prep(int wid_s, const Args& a, unsigned char* shm) {
;     ...
;         float* XF = (float*)(a.ws + WS_XF); bf16_t* XB = (bf16_t*)(a.ws + WS_XB);
;         for (size_t i = (size_t)bx * NTHREADS + tid; i < (size_t)MT * DM / 4; i += (size_t)G * NTHREADS) {
;             const f32x4 v = *(const f32x4*)(a.x + 4 * i); *(u32x2*)(XB + 4 * i) = pack4(v); }
;     }
;     { bf16_t* WPT = (bf16_t*)(a.ws + WS_WPT);
;       for (int i = bx * NTHREADS + tid; i < DEPTH * 4 * 128 * 64; i += G * NTHREADS) { const int c2 = i & 63, d = (i >> 6) & 127, lg = i >> 13;
.LBB0_73:
	v_readlane_b32 s0, v253, 0
	v_readlane_b32 s1, v253, 1
	s_lshl_b64 s[0:1], s[0:1], 9
	v_ashrrev_i32_e32 v37, 31, v36
	s_waitcnt vmcnt(11)
	v_lshl_add_u64 v[2:3], s[0:1], 0, v[36:37]
	s_mov_b64 s[0:1], 0x400000
	v_cmp_gt_u64_e32 vcc, s[0:1], v[2:3]
	s_and_saveexec_b64 s[0:1], vcc
	s_cbranch_execz .LBB0_76
	v_readlane_b32 s10, v253, 0
	s_ashr_i32 s77, s76, 31
	v_readlane_b32 s11, v253, 1
	s_lshl_b64 s[6:7], s[76:77], 9
	s_lshl_b64 s[8:9], s[10:11], 13
	s_add_u32 s8, s80, s8
	s_addc_u32 s9, s81, s9
	v_lshl_add_u64 v[4:5], v[36:37], 4, s[8:9]
	s_lshl_b64 s[8:9], s[76:77], 13
	s_lshl_b64 s[10:11], s[10:11], 12
	s_add_u32 s10, s72, s10
	s_addc_u32 s11, s73, s11
	s_waitcnt vmcnt(10)
	v_lshl_add_u64 v[6:7], v[36:37], 3, s[10:11]
	s_mov_b64 s[10:11], 0x14e00000
	v_lshl_add_u64 v[6:7], v[6:7], 0, s[10:11]
	s_lshl_b64 s[10:11], s[76:77], 12
	s_mov_b32 s14, 4
	s_waitcnt vmcnt(0)
.LBB0_75:
	global_load_dwordx4 v[8:11], v[4:5], off
	v_lshl_add_u64 v[4:5], v[4:5], 0, s[8:9]
	global_load_dwordx4 v[12:15], v[4:5], off
	v_lshl_add_u64 v[4:5], v[4:5], 0, s[8:9]
	global_load_dwordx4 v[16:19], v[4:5], off
	v_lshl_add_u64 v[4:5], v[4:5], 0, s[8:9]
	global_load_dwordx4 v[20:23], v[4:5], off
	v_lshl_add_u64 v[4:5], v[4:5], 0, s[8:9]
	global_load_dwordx4 v[24:27], v[4:5], off
	v_lshl_add_u64 v[4:5], v[4:5], 0, s[8:9]
	global_load_dwordx4 v[28:31], v[4:5], off
	v_lshl_add_u64 v[4:5], v[4:5], 0, s[8:9]
	global_load_dwordx4 v[40:43], v[4:5], off
	v_lshl_add_u64 v[4:5], v[4:5], 0, s[8:9]
	global_load_dwordx4 v[44:47], v[4:5], off
	v_lshl_add_u64 v[4:5], v[4:5], 0, s[8:9]
	s_waitcnt vmcnt(7)
	v_cvt_pkrtz_f16_f32 v8, v8, v9
	v_cvt_pkrtz_f16_f32 v9, v10, v11
	global_store_dwordx2 v[6:7], v[8:9], off
	v_lshl_add_u64 v[6:7], v[6:7], 0, s[10:11]
	s_waitcnt vmcnt(7)
	v_cvt_pkrtz_f16_f32 v12, v12, v13
	v_cvt_pkrtz_f16_f32 v13, v14, v15
	global_store_dwordx2 v[6:7], v[12:13], off
	v_lshl_add_u64 v[6:7], v[6:7], 0, s[10:11]
	s_waitcnt vmcnt(7)
	v_cvt_pkrtz_f16_f32 v16, v16, v17
	v_cvt_pkrtz_f16_f32 v17, v18, v19
	global_store_dwordx2 v[6:7], v[16:17], off
	v_lshl_add_u64 v[6:7], v[6:7], 0, s[10:11]
	s_waitcnt vmcnt(7)
	v_cvt_pkrtz_f16_f32 v20, v20, v21
	v_cvt_pkrtz_f16_f32 v21, v22, v23
	global_store_dwordx2 v[6:7], v[20:21], off
	v_lshl_add_u64 v[6:7], v[6:7], 0, s[10:11]
	s_waitcnt vmcnt(7)
	v_cvt_pkrtz_f16_f32 v24, v24, v25
	v_cvt_pkrtz_f16_f32 v25, v26, v27
	global_store_dwordx2 v[6:7], v[24:25], off
	v_lshl_add_u64 v[6:7], v[6:7], 0, s[10:11]
	s_waitcnt vmcnt(7)
	v_cvt_pkrtz_f16_f32 v28, v28, v29
	v_cvt_pkrtz_f16_f32 v29, v30, v31
	global_store_dwordx2 v[6:7], v[28:29], off
	v_lshl_add_u64 v[6:7], v[6:7], 0, s[10:11]
	s_waitcnt vmcnt(7)
	v_cvt_pkrtz_f16_f32 v40, v40, v41
	v_cvt_pkrtz_f16_f32 v41, v42, v43
	global_store_dwordx2 v[6:7], v[40:41], off
	v_lshl_add_u64 v[6:7], v[6:7], 0, s[10:11]
	s_waitcnt vmcnt(7)
	v_cvt_pkrtz_f16_f32 v44, v44, v45
	v_cvt_pkrtz_f16_f32 v45, v46, v47
	global_store_dwordx2 v[6:7], v[44:45], off
	v_lshl_add_u64 v[6:7], v[6:7], 0, s[10:11]
	s_sub_u32 s14, s14, 1
	s_cmp_lg_u32 s14, 0
	s_cbranch_scc1 .LBB0_75
.LBB0_76:
	s_or_b64 exec, exec, s[0:1]
	v_readlane_b32 s0, v253, 0
	s_lshl_b32 s6, s76, 9
	v_readlane_b32 s1, v253, 1
	s_sub_u32 s0, 0xff, s0
	s_nop 0
	v_lshl_add_u32 v2, s0, 9, v36
	s_mov_b32 s0, 0x20000
	v_cmp_gt_i32_e32 vcc, s0, v2
	v_lshlrev_b32_e32 v3, 1, v36
	s_and_saveexec_b64 s[0:1], vcc
	s_cbranch_execz .LBB0_79
	v_readlane_b32 s10, v253, 0
	s_add_u32 s8, s72, 0x2bd7a000
	v_readlane_b32 s11, v253, 1
	s_addc_u32 s9, s73, 0
	s_sub_u32 s10, 0xff, s10
	s_waitcnt vmcnt(10)
	v_lshl_add_u32 v6, s10, 10, v3
	s_lshl_b32 s7, s76, 10
	s_mov_b64 s[10:11], 0
	v_mov_b32_e32 v5, 0
	s_mov_b32 s12, 0x1ffff
	v_mov_b32_e32 v7, v2

; #define bx (opaque_bx())
; #define ws (opaque_base(a.ws))
; __device__ __forceinline__ void phase_prep(int wid_s, const Args& a, unsigned char* shm) {
;     ...
;     { float* rope = (float*)(a.ws + WS_ROPE);
;       for (int i = bx * NTHREADS + tid; i < 2048 * 32; i += G * NTHREADS) { const int pos = i >> 5, k = i & 31;
;           const double inv = exp(-(double)k * (9.210340371976184 / 32.0)); double s, c; sincos_d((double)pos * inv, s, c); rope[2 * i] = (float)c; rope[2 * i + 1] = (float)s; } }
.LBB0_79:
	s_or_b64 exec, exec, s[0:1]
	s_mov_b32 s0, 0x10000
	v_cmp_gt_i32_e32 vcc, s0, v2
	s_and_saveexec_b64 s[8:9], vcc
	s_cbranch_execz .LBB0_88
	v_and_b32_e32 v4, 31, v35
	s_mov_b32 s0, 0xbbb55516
	v_cvt_f64_u32_e32 v[4:5], v4
	s_mov_b32 s1, 0xbfd26bb1
	s_waitcnt vmcnt(10)
	v_mul_f64 v[8:9], v[4:5], s[0:1]
	s_mov_b32 s0, 0x652b82fe
	s_mov_b32 s1, 0x3ff71547
	v_mul_f64 v[4:5], v[8:9], s[0:1]
	s_mov_b32 s0, 0xfefa39ef
	s_waitcnt vmcnt(9)
	v_rndne_f64_e32 v[10:11], v[4:5]
	s_mov_b32 s1, 0xbfe62e42
	v_fma_f64 v[12:13], s[0:1], v[10:11], v[8:9]
	s_mov_b32 s0, 0x3b39803f
	s_mov_b32 s1, 0xbc7abc9e
	v_fmac_f64_e32 v[12:13], s[0:1], v[10:11]
	s_mov_b32 s0, 0x6a5dcb37
	v_mov_b32_e32 v4, 0xfca7ab0c
	v_mov_b32_e32 v5, 0x3e928af3
	s_mov_b32 s1, 0x3e5ade15
	v_fmac_f64_e32 v[4:5], s[0:1], v[12:13]
	v_mov_b32_e32 v6, 0x623fde64
	v_mov_b32_e32 v7, 0x3ec71dee
	v_fmac_f64_e32 v[6:7], v[12:13], v[4:5]
	v_mov_b32_e32 v4, 0x7c89e6b0
	v_mov_b32_e32 v5, 0x3efa0199
	v_fmac_f64_e32 v[4:5], v[12:13], v[6:7]
	v_mov_b32_e32 v6, 0x14761f6e
	v_mov_b32_e32 v7, 0x3f2a01a0
	v_fmac_f64_e32 v[6:7], v[12:13], v[4:5]
	s_waitcnt vmcnt(8)
	v_mov_b32_e32 v14, 0x1852b7b0
	v_mov_b32_e32 v15, 0x3f56c16c
	v_mov_b32_e32 v4, 0x11122322
	v_mov_b32_e32 v5, 0x3f811111
	v_fmac_f64_e32 v[14:15], v[12:13], v[6:7]
	v_mov_b64_e32 v[16:17], v[4:5]
	v_mov_b32_e32 v6, 0x555502a1
	v_mov_b32_e32 v7, 0x3fa55555
	v_fmac_f64_e32 v[16:17], v[12:13], v[14:15]
	v_mov_b64_e32 v[14:15], v[6:7]
	v_fmac_f64_e32 v[14:15], v[12:13], v[16:17]
	v_mov_b32_e32 v16, 0x55555511
	v_mov_b32_e32 v17, 0x3fc55555
	v_fmac_f64_e32 v[16:17], v[12:13], v[14:15]
	v_mov_b32_e32 v14, 11
	v_mov_b32_e32 v15, 0x3fe00000
	v_fmac_f64_e32 v[14:15], v[12:13], v[16:17]
	s_mov_b32 s0, 0
	v_fma_f64 v[14:15], v[12:13], v[14:15], 1.0
	s_mov_b32 s1, 0x40900000
	v_fma_f64 v[12:13], v[12:13], v[14:15], 1.0
	v_cvt_i32_f64_e32 v4, v[10:11]
	v_cmp_nlt_f64_e32 vcc, s[0:1], v[8:9]
	s_mov_b32 s0, 0
	v_ldexp_f64 v[10:11], v[12:13], v4
	v_mov_b32_e32 v4, 0x7ff00000
	s_mov_b32 s1, 0xc090cc00
	s_add_u32 s10, s72, 0x2b9d6000
	v_cndmask_b32_e32 v4, v4, v11, vcc
	v_cmp_ngt_f64_e64 s[0:1], s[0:1], v[8:9]
	s_addc_u32 s11, s73, 0
	s_and_b64 vcc, s[0:1], vcc
	v_cndmask_b32_e64 v9, 0, v4, s[0:1]
	v_readlane_b32 s0, v253, 0
	v_readlane_b32 s1, v253, 1
	s_sub_u32 s0, 0xff, s0
	s_mov_b32 s12, 0x6dc9c883
	s_mov_b32 s14, 0x54442d18
	s_mov_b32 s16, 0x33145c07
	s_mov_b32 s18, 0xe733b81f
	s_waitcnt vmcnt(7)
	v_mov_b32_e32 v18, 0x1a01a01a
	v_mov_b32_e32 v20, 0x55555555
	v_cndmask_b32_e32 v8, 0, v10, vcc
	v_lshl_add_u32 v10, s0, 10, v3
	s_lshl_b32 s7, s76, 10
	s_mov_b64 s[0:1], 0
	s_mov_b32 s13, 0x3fe45f30
	s_mov_b32 s15, 0xbff921fb
	s_movk_i32 s26, 0xffe0
	s_mov_b32 s17, 0xbc91a626
	v_mov_b32_e32 v12, 0x13a86d09
	v_mov_b32_e32 v13, 0x3de61246
	s_mov_b32 s19, 0xbd6ae7f3
	v_mov_b32_e32 v14, 0x67f544e4
	v_mov_b32_e32 v15, 0xbe5ae645
	v_mov_b32_e32 v16, 0xa556c734
	v_mov_b32_e32 v17, 0x3ec71de3
	v_mov_b32_e32 v19, 0xbf2a01a0
	v_mov_b32_e32 v4, 0x11111111
	v_mov_b32_e32 v21, 0xbfc55555
	s_waitcnt vmcnt(6)
	v_mov_b32_e32 v22, 0xa8c07c9d
	v_mov_b32_e32 v23, 0xbda93974
	s_mov_b32 s21, 0x3d2ae7f3
	s_mov_b32 s20, s18
	v_mov_b32_e32 v24, 0xeff8d898
	v_mov_b32_e32 v25, 0x3e21eed8
	s_waitcnt vmcnt(5)
	v_mov_b32_e32 v26, 0xb7789f5c
	v_mov_b32_e32 v27, 0xbe927e4f
	v_mov_b32_e32 v29, 0x3efa01a0
	v_mov_b32_e32 v28, v18
	s_waitcnt vmcnt(4)
	v_mov_b32_e32 v30, 0x16c16c17
	v_mov_b32_e32 v31, 0xbf56c16c
	v_mov_b32_e32 v6, v20
	s_mov_b32 s27, 0xffff
	v_mov_b32_e32 v3, v2
	s_branch .LBB0_83

; #define LAS __attribute__((address_space(3)))
; __device__ __forceinline__ float h2f(unsigned h) { float r; asm volatile("v_cvt_f32_f16 %0, %1" : "=v"(r) : "v"(h)); return r; }
; __device__ __forceinline__ void phase_pool(int wid_s, unsigned char* shm, const float* UPi, const bf16_t* WPT, bf16_t* MIX) {
;     ...
;     for (int item = blockIdx.x; item < 512; item += gridDim.x) {
;         const int tile = item >> 2, gi = item & 3, w = 2 << gi, tok0 = tile * 64, pos0 = tok0 & (SEQ - 1);
;         __syncthreads();
;         u32x2 hw[5]; u32x4 ww[4];
; #pragma unroll
;         for (int i = 0; i < 5; ++i) { const int idx = i * NTHREADS + tid, r = (idx < 79 * 32) ? (idx >> 5) : 78, c4 = idx & 31; const int rr = (pos0 - 15 + r >= 0) ? r : 15;
;             hw[i] = *(const u32x2*)((const bf16_t*)UPi + (size_t)(tok0 - 15 + rr) * 512 + gi * 128 + 4 * c4); }
; #pragma unroll
;         for (int i = 0; i < 4; ++i) { const int idx = i * NTHREADS + tid, d = idx >> 4, c8 = idx & 15; ww[i] = *(const u32x4*)(WPT + (size_t)gi * 128 * 128 + d * 128 + 8 * c8); }
; #pragma unroll
;         for (int i = 0; i < 5; ++i) { const int idx = i * NTHREADS + tid, r = idx >> 5, c4 = idx & 31;
;             if (idx < 79 * 32) { f32x4 v = {h2f(hw[i].x), h2f(hw[i].x >> 16), h2f(hw[i].y), h2f(hw[i].y >> 16)}; if (pos0 - 15 + r < 0) v = (f32x4){0.f, 0.f, 0.f, 0.f};
;                 *(f32x4*)(Us + r * 128 + 4 * c4) = v; } }
; #pragma unroll
;         for (int i = 0; i < 4; ++i) { const int idx = i * NTHREADS + tid, d = idx >> 4, c8 = idx & 15; *(LAS u32x4*)(Wt + d * 136 + 8 * c8) = ww[i]; }
.LBB0_501:
	s_mov_b64 s[2:3], s[72:73]
	s_mov_b64 s[4:5], s[72:73]
	s_mov_b64 s[14:15], s[72:73]
	v_mov_b32_e32 v4, v240
	s_and_b64 vcc, exec, s[0:1]
	s_waitcnt lgkmcnt(0)
	s_barrier
	s_branch .LBB0_516
.Lpool_in_glu:
	s_mov_b64 s[2:3], s[72:73]
	s_mov_b64 s[4:5], s[72:73]
	s_mov_b64 s[14:15], s[72:73]
	v_mov_b32_e32 v4, v240
	s_lshl_b64 s[0:1], s[86:87], 17
	s_add_u32 s0, s4, s0
	v_readlane_b32 s4, v253, 37
	s_addc_u32 s1, s5, s1
	v_lshlrev_b32_e32 v0, 2, v4
	s_waitcnt vmcnt(0)
	v_or_b32_e32 v8, s4, v4
	v_add_u32_e32 v17, 0x200, v8
	v_min_i32_e32 v18, 0x9df, v17
	v_ashrrev_i32_e32 v48, 5, v18
	v_add_u32_e32 v18, 0x400, v8
	v_min_i32_e32 v19, 0x9df, v18
	v_ashrrev_i32_e32 v9, 6, v8
	v_lshlrev_b32_e32 v6, 4, v8
	v_ashrrev_i32_e32 v49, 5, v19
	v_add_u32_e32 v19, 0x600, v8
	v_and_b32_e32 v6, 0xf0, v6
	v_mov_b32_e32 v7, v2
	v_lshlrev_b32_e32 v13, 4, v9
	v_min_i32_e32 v22, 0x9df, v19
	v_add_u32_e32 v30, 0x800, v8
	v_and_b32_e32 v5, 15, v4
	v_and_b32_e32 v3, 0x7c, v0
	v_lshl_add_u64 v[6:7], s[0:1], 0, v[6:7]
	s_mov_b64 s[0:1], 0x2bd7a000
	v_ashrrev_i32_e32 v50, 5, v22
	v_min_i32_e32 v22, 0x9df, v30
	v_ashrrev_i32_e32 v56, 5, v30
	v_and_b32_e32 v30, 0xffffffc0, v13
	v_lshlrev_b32_e32 v0, 1, v3
	v_mov_b32_e32 v1, v2
	v_lshl_add_u64 v[20:21], v[6:7], 0, s[0:1]
	v_lshl_add_u32 v6, v3, 2, 0
	v_lshlrev_b32_e32 v3, 4, v4
	s_movk_i32 s9, 0x110
	v_or_b32_e32 v32, v30, v5
	v_and_b32_e32 v10, 63, v4
	v_lshl_add_u64 v[0:1], s[2:3], 0, v[0:1]
	s_mov_b64 s[2:3], 0x20600000
	v_and_b32_e32 v3, 0xf0, v3
	s_movk_i32 s0, 0x9e0
	v_mul_lo_u32 v85, v32, s9
	v_or_b32_e32 v33, 16, v32
	v_or_b32_e32 v32, 32, v32
	v_lshl_add_u64 v[0:1], v[0:1], 0, s[2:3]
	v_lshlrev_b32_e32 v11, 3, v8
	v_add_u32_e32 v7, 0, v3
	v_lshlrev_b32_e32 v3, 3, v9
	v_lshlrev_b32_e32 v12, 3, v10
	v_cmp_gt_i32_e32 vcc, s0, v8
	s_movk_i32 s0, 0x7e0
	s_movk_i32 s2, 0x5e0
	s_movk_i32 s4, 0x3e0
	s_movk_i32 s6, 0x1e0
	v_lshlrev_b32_e32 v57, 12, v9
	s_movk_i32 s8, 0x880
	v_mul_lo_u32 v87, v32, s9
	v_or_b32_e32 v32, 48, v13
	v_add_u32_e32 v46, 0, v12
	v_lshlrev_b32_e32 v10, 2, v10
	v_and_or_b32 v47, v13, 48, v5
	v_and_b32_e32 v15, 48, v4
	v_lshrrev_b32_e32 v4, 2, v4
	v_ashrrev_i32_e32 v51, 5, v22
	v_and_b32_e32 v22, 0xffffff80, v11
	v_ashrrev_i32_e32 v52, 5, v8
	v_cmp_gt_i32_e64 s[0:1], s0, v8
	v_ashrrev_i32_e32 v53, 5, v17
	v_cmp_gt_i32_e64 s[2:3], s2, v8
	v_ashrrev_i32_e32 v54, 5, v18
	v_cmp_gt_i32_e64 s[4:5], s4, v8
	v_ashrrev_i32_e32 v55, 5, v19
	v_cmp_gt_i32_e64 s[6:7], s6, v8
	v_lshrrev_b32_e32 v8, 4, v8
	v_lshrrev_b32_e32 v17, 4, v17
	v_lshrrev_b32_e32 v18, 4, v18
	v_lshrrev_b32_e32 v19, 4, v19
	v_mul_lo_u32 v9, v9, s8
	v_or_b32_e32 v58, 1, v3
	v_or_b32_e32 v59, 2, v3
	v_or_b32_e32 v60, 3, v3
	v_or_b32_e32 v61, 4, v3
	v_or_b32_e32 v62, 5, v3
	v_or_b32_e32 v63, 6, v3
	v_or_b32_e32 v64, 7, v3
	v_or_b32_e32 v5, v32, v5
	v_or_b32_e32 v12, v57, v12
	v_readlane_b32 s8, v253, 50
	v_sub_u32_e32 v10, v46, v10
	v_mad_u32_u24 v14, v47, s9, 0
	v_add_u32_e32 v16, 0, v15
	v_and_b32_e32 v4, 12, v4
	v_add_u32_e32 v24, 0x1000, v22
	v_add_u32_e32 v26, 0x2000, v22
	v_add_u32_e32 v28, 0x3000, v22
	v_lshlrev_b32_e32 v11, 9, v52
	v_lshlrev_b32_e32 v34, 9, v53
	v_lshlrev_b32_e32 v35, 9, v54
	v_lshlrev_b32_e32 v36, 9, v55
	v_lshlrev_b32_e32 v37, 9, v56
	v_mul_lo_u32 v8, v8, s9
	v_mul_lo_u32 v17, v17, s9
	v_mul_lo_u32 v18, v18, s9
	v_mul_lo_u32 v19, v19, s9
	v_lshlrev_b32_e32 v38, 9, v58
	v_mul_lo_u32 v39, v58, s9
	v_lshlrev_b32_e32 v40, 9, v59
	v_lshlrev_b32_e32 v41, 9, v60
	v_lshlrev_b32_e32 v42, 9, v61
	v_lshlrev_b32_e32 v43, 9, v62
	v_lshlrev_b32_e32 v44, 9, v63
	v_lshlrev_b32_e32 v45, 9, v64
	v_mul_lo_u32 v86, v33, s9
	v_mul_lo_u32 v5, v5, s9
	v_add_u32_e32 v65, s8, v12
	v_readlane_b32 s8, v253, 0
	v_ashrrev_i32_e32 v23, 31, v22
	v_ashrrev_i32_e32 v25, 31, v24
	v_ashrrev_i32_e32 v27, 31, v26
	v_ashrrev_i32_e32 v29, 31, v28
	v_ashrrev_i32_e32 v31, 31, v30
	v_ashrrev_i32_e32 v33, 31, v32
	v_add_u32_e32 v66, v6, v11
	v_add_u32_e32 v67, v6, v34
	v_add_u32_e32 v68, v6, v35
	v_add_u32_e32 v69, v6, v36
	v_add_u32_e32 v70, v6, v37
	v_add_u32_e32 v71, v7, v8
	v_add_u32_e32 v72, v7, v17
	v_add_u32_e32 v73, v7, v18
	v_add_u32_e32 v74, v7, v19
	v_add_u32_e32 v75, v10, v9
	v_add_u32_e32 v76, v46, v38
	v_add_u32_e32 v77, v10, v39
	v_add_u32_e32 v78, v46, v40
	v_add_u32_e32 v79, v46, v41
	v_add_u32_e32 v80, v46, v42
	v_add_u32_e32 v81, v46, v43
	v_add_u32_e32 v82, v46, v44
	v_add_u32_e32 v83, v46, v45
	v_add_u32_e32 v84, v14, v15
	v_lshlrev_b32_e32 v34, 1, v4
	v_add_u32_e32 v85, v16, v85
	v_add_u32_e32 v86, v16, v86
	v_add_u32_e32 v87, v16, v87
	v_add_u32_e32 v88, v16, v5
	s_add_i32 s18, s8, 0xffffff80
	v_readlane_b32 s9, v253, 1

; #define LAS __attribute__((address_space(3)))
; __device__ __forceinline__ unsigned cvt_pk_bf16(float lo, float hi) { return __builtin_bit_cast(unsigned, __builtin_amdgcn_cvt_pkrtz(lo, hi)); }
; __device__ __forceinline__ void phase_pool(int wid_s, unsigned char* shm, const float* UPi, const bf16_t* WPT, bf16_t* MIX) {
;     ...
;         { const int c2 = tid & 63, rs = tid >> 6;
;           f32x2 sum = {0.f, 0.f};
;           for (int k = 1; k < w; ++k) { const f32x2 u = *(const f32x2*)(Us + (8 * rs + 15 - k) * 128 + 2 * c2); sum += u; }
; #pragma unroll
;           for (int rr = 0; rr < 8; ++rr) { const int r = 8 * rs + rr, pos = pos0 + r;
;               const f32x2 u = *(const f32x2*)(Us + (r + 15) * 128 + 2 * c2); sum += u;
;               const float rcw = __builtin_amdgcn_rcpf((float)((pos + 1 < w) ? pos + 1 : w));
;               *(LAS unsigned*)(Ds + r * 136 + 2 * c2) = cvt_pk_bf16(sum.x * rcw - u.x, sum.y * rcw - u.y);
;               const f32x2 uo = *(const f32x2*)(Us + (r + 15 - (w - 1)) * 128 + 2 * c2); sum -= uo; } }
;         __syncthreads();
.LBB0_510:
	ds_read_b64 v[8:9], v6
	s_add_i32 s10, s10, -1
	v_add_u32_e32 v6, 0xfffffe00, v6
	s_cmp_eq_u32 s10, 0
	s_waitcnt lgkmcnt(0)
	v_pk_add_f32 v[4:5], v[4:5], v[8:9]
	s_cbranch_scc0 .LBB0_510
	s_or_b32 s10, s20, 1
	v_add_u32_e32 v6, s10, v3
	v_min_i32_e32 v6, s9, v6
	v_cvt_f32_i32_e32 v8, v6
	v_add_u32_e32 v6, v46, v57
	ds_read_b64 v[6:7], v6 offset:7680
	v_subrev_u32_e32 v9, s9, v3
	v_rcp_iflag_f32_e32 v8, v8
	v_lshl_add_u32 v9, v9, 9, v46
	v_or_b32_e32 v44, s19, v47
	s_waitcnt lgkmcnt(0)
	v_pk_add_f32 v[4:5], v[4:5], v[6:7]
	v_ashrrev_i32_e32 v45, 31, v44
	v_fma_f32 v6, v8, v4, -v6
	v_fma_f32 v7, v8, v5, -v7
	v_cvt_pkrtz_f16_f32 v6, v6, v7
	ds_write_b32 v75, v6 offset:40448
	v_add_u32_e32 v6, s10, v58
	v_min_i32_e32 v6, s9, v6
	v_cvt_f32_i32_e32 v10, v6
	ds_read_b64 v[6:7], v9 offset:8192
	ds_read_b64 v[8:9], v76 offset:7680
	v_lshlrev_b64 v[44:45], 12, v[44:45]
	v_lshl_add_u64 v[44:45], s[14:15], 0, v[44:45]
	v_rcp_iflag_f32_e32 v10, v10
	s_waitcnt lgkmcnt(1)
	v_pk_add_f32 v[4:5], v[4:5], v[6:7] neg_lo:[0,1] neg_hi:[0,1]
	v_mov_b32_e32 v35, v2
	s_waitcnt lgkmcnt(0)
	v_pk_add_f32 v[4:5], v[4:5], v[8:9]
	s_addk_i32 s18, 0x80
	v_fma_f32 v6, v10, v4, -v8
	v_fma_f32 v7, v10, v5, -v9
	v_cvt_pkrtz_f16_f32 v6, v6, v7
	v_add_u32_e32 v7, s10, v59
	v_min_i32_e32 v7, s9, v7
	ds_write_b32 v77, v6 offset:40448
	v_subrev_u32_e32 v6, s9, v58
	v_cvt_f32_i32_e32 v10, v7
	v_lshl_add_u32 v6, v6, 9, v46
	ds_read_b64 v[6:7], v6 offset:8192
	ds_read_b64 v[8:9], v78 offset:7680
	v_rcp_iflag_f32_e32 v10, v10
	s_waitcnt lgkmcnt(1)
	v_pk_add_f32 v[4:5], v[4:5], v[6:7] neg_lo:[0,1] neg_hi:[0,1]
	s_waitcnt lgkmcnt(0)
	v_pk_add_f32 v[4:5], v[4:5], v[8:9]
	s_nop 0
	v_fma_f32 v6, v10, v4, -v8
	v_fma_f32 v7, v10, v5, -v9
	v_cvt_pkrtz_f16_f32 v6, v6, v7
	v_add_u32_e32 v7, s10, v60
	v_min_i32_e32 v7, s9, v7
	ds_write_b32 v77, v6 offset:40720
	v_subrev_u32_e32 v6, s9, v59
	v_cvt_f32_i32_e32 v10, v7
	v_lshl_add_u32 v6, v6, 9, v46
	ds_read_b64 v[6:7], v6 offset:8192
	ds_read_b64 v[8:9], v79 offset:7680
	v_rcp_iflag_f32_e32 v10, v10
	s_waitcnt lgkmcnt(1)
	v_pk_add_f32 v[4:5], v[4:5], v[6:7] neg_lo:[0,1] neg_hi:[0,1]
	s_waitcnt lgkmcnt(0)
	v_pk_add_f32 v[4:5], v[4:5], v[8:9]
	s_nop 0
	v_fma_f32 v6, v10, v4, -v8
	v_fma_f32 v7, v10, v5, -v9
	v_cvt_pkrtz_f16_f32 v6, v6, v7
	v_add_u32_e32 v7, s10, v61
	v_min_i32_e32 v7, s9, v7
	ds_write_b32 v77, v6 offset:40992
	v_subrev_u32_e32 v6, s9, v60
	v_cvt_f32_i32_e32 v10, v7
	v_lshl_add_u32 v6, v6, 9, v46
	ds_read_b64 v[6:7], v6 offset:8192
	ds_read_b64 v[8:9], v80 offset:7680
	v_rcp_iflag_f32_e32 v10, v10
	s_waitcnt lgkmcnt(1)
	v_pk_add_f32 v[4:5], v[4:5], v[6:7] neg_lo:[0,1] neg_hi:[0,1]
	s_waitcnt lgkmcnt(0)
	v_pk_add_f32 v[4:5], v[4:5], v[8:9]
	s_nop 0
	v_fma_f32 v6, v10, v4, -v8
	v_fma_f32 v7, v10, v5, -v9
	v_cvt_pkrtz_f16_f32 v6, v6, v7
	v_add_u32_e32 v7, s10, v62
	v_min_i32_e32 v7, s9, v7
	ds_write_b32 v77, v6 offset:41264
	v_subrev_u32_e32 v6, s9, v61
	v_cvt_f32_i32_e32 v10, v7
	v_lshl_add_u32 v6, v6, 9, v46
	ds_read_b64 v[6:7], v6 offset:8192
	ds_read_b64 v[8:9], v81 offset:7680
	v_rcp_iflag_f32_e32 v10, v10
	s_waitcnt lgkmcnt(1)
	v_pk_add_f32 v[4:5], v[4:5], v[6:7] neg_lo:[0,1] neg_hi:[0,1]
	s_waitcnt lgkmcnt(0)
	v_pk_add_f32 v[4:5], v[4:5], v[8:9]
	s_nop 0
	v_fma_f32 v6, v10, v4, -v8
	v_fma_f32 v7, v10, v5, -v9
	v_cvt_pkrtz_f16_f32 v6, v6, v7
	v_add_u32_e32 v7, s10, v63
	v_min_i32_e32 v7, s9, v7
	ds_write_b32 v77, v6 offset:41536
	v_subrev_u32_e32 v6, s9, v62
	v_cvt_f32_i32_e32 v10, v7
	v_lshl_add_u32 v6, v6, 9, v46
	ds_read_b64 v[6:7], v6 offset:8192
	ds_read_b64 v[8:9], v82 offset:7680
	v_rcp_iflag_f32_e32 v10, v10
	s_waitcnt lgkmcnt(1)
	v_pk_add_f32 v[4:5], v[4:5], v[6:7] neg_lo:[0,1] neg_hi:[0,1]
	s_waitcnt lgkmcnt(0)
	v_pk_add_f32 v[4:5], v[4:5], v[8:9]
	s_nop 0
	v_fma_f32 v6, v10, v4, -v8
	v_fma_f32 v7, v10, v5, -v9
	v_cvt_pkrtz_f16_f32 v6, v6, v7
	v_add_u32_e32 v7, s10, v64
	v_min_i32_e32 v7, s9, v7
	ds_write_b32 v77, v6 offset:41808
	v_subrev_u32_e32 v6, s9, v63
	v_cvt_f32_i32_e32 v10, v7
	v_lshl_add_u32 v6, v6, 9, v46
	ds_read_b64 v[6:7], v6 offset:8192
	ds_read_b64 v[8:9], v83 offset:7680
	s_lshl_b32 s10, s8, 1
	v_rcp_iflag_f32_e32 v10, v10
	v_lshl_add_u64 v[44:45], v[44:45], 0, s[10:11]
	s_waitcnt lgkmcnt(1)
	v_pk_add_f32 v[4:5], v[4:5], v[6:7] neg_lo:[0,1] neg_hi:[0,1]
	v_lshl_add_u64 v[44:45], v[44:45], 0, v[34:35]
	s_waitcnt lgkmcnt(0)
	v_pk_add_f32 v[4:5], v[4:5], v[8:9]
	s_mov_b64 s[8:9], 0x22600800
	v_fma_f32 v4, v10, v4, -v8
	v_fma_f32 v5, v10, v5, -v9
	v_cvt_pkrtz_f16_f32 v4, v4, v5
	ds_write_b32 v77, v4 offset:42080
	s_waitcnt lgkmcnt(0)
	s_barrier
; #define LAS __attribute__((address_space(3)))
; __device__ __forceinline__ f32x4 mfma16(bf16x8 a, bf16x8 b, f32x4 c) { return __builtin_amdgcn_mfma_f32_16x16x32_f16(__builtin_bit_cast(f16x8, a), __builtin_bit_cast(f16x8, b), c, 0, 0, 0); }
; __device__ __forceinline__ u32x2 pack4(f32x4 v) { u32x2 r; r.x = cvt_pk_bf16(v[0], v[1]); r.y = cvt_pk_bf16(v[2], v[3]); return r; }
; __device__ __forceinline__ void phase_pool(int wid_s, unsigned char* shm, const float* UPi, const bf16_t* WPT, bf16_t* MIX) {
;     ...
;         { const int mt = wid & 3, nt0 = (wid >> 2) * 4;
;           bf16x8 bfr[4];
; #pragma unroll
;           for (int ks = 0; ks < 4; ++ks) bfr[ks] = *(const LAS bf16x8*)(Ds + (16 * mt + fr) * 136 + 32 * ks + 8 * fq);
; #pragma unroll
;           for (int j = 0; j < 4; ++j) { const int nt = nt0 + j; f32x4 o = {0.f, 0.f, 0.f, 0.f};
; #pragma unroll
;               for (int ks = 0; ks < 4; ++ks) { const bf16x8 af = *(const LAS bf16x8*)(Wt + (16 * nt + fr) * 136 + 32 * ks + 8 * fq);
;                   o = mfma16(af, bfr[ks], o); asm volatile("" :: "v"(af), "v"(bfr[ks]), "v"(o)); }
;               *(u32x2*)(MIX + (size_t)(tok0 + 16 * mt + fr) * DM + 1024 + gi * 128 + 16 * nt + 4 * fq) = pack4(o); } }
;     }
	ds_read_b128 v[4:7], v85 offset:57856
	ds_read_b128 v[8:11], v84 offset:40448
	ds_read_b128 v[12:15], v84 offset:40512
	ds_read_b128 v[16:19], v84 offset:40576
	ds_read_b128 v[36:39], v84 offset:40640
	s_waitcnt lgkmcnt(3)
	v_mfma_f32_16x16x32_f16 v[40:43], v[4:7], v[8:11], 0
	ds_read_b128 v[4:7], v85 offset:57920
	v_lshl_add_u64 v[44:45], v[44:45], 0, s[8:9]
	s_waitcnt lgkmcnt(0)
	v_mfma_f32_16x16x32_f16 v[40:43], v[4:7], v[12:15], v[40:43]
	ds_read_b128 v[4:7], v85 offset:57984
	v_lshl_add_u64 v[90:91], v[30:31], 1, v[44:45]
	s_waitcnt lgkmcnt(0)
	v_mfma_f32_16x16x32_f16 v[40:43], v[4:7], v[16:19], v[40:43]
	ds_read_b128 v[4:7], v85 offset:58048
	s_cmpk_gt_i32 s18, 0x1ff
	s_waitcnt lgkmcnt(0)
	v_mfma_f32_16x16x32_f16 v[40:43], v[4:7], v[36:39], v[40:43]
	s_nop 7
	v_cvt_pkrtz_f16_f32 v4, v40, v41
	v_cvt_pkrtz_f16_f32 v5, v42, v43
	flat_store_dwordx2 v[90:91], v[4:5]
	ds_read_b128 v[4:7], v86 offset:57856
	s_waitcnt lgkmcnt(0)
	v_mfma_f32_16x16x32_f16 v[40:43], v[4:7], v[8:11], 0
	ds_read_b128 v[4:7], v86 offset:57920
	s_waitcnt lgkmcnt(0)
	v_mfma_f32_16x16x32_f16 v[40:43], v[4:7], v[12:15], v[40:43]
	ds_read_b128 v[4:7], v86 offset:57984
	s_waitcnt lgkmcnt(0)
	v_mfma_f32_16x16x32_f16 v[40:43], v[4:7], v[16:19], v[40:43]
	ds_read_b128 v[4:7], v86 offset:58048
	s_waitcnt lgkmcnt(0)
	v_mfma_f32_16x16x32_f16 v[40:43], v[4:7], v[36:39], v[40:43]
	s_nop 7
	v_cvt_pkrtz_f16_f32 v4, v40, v41
	v_cvt_pkrtz_f16_f32 v5, v42, v43
	flat_store_dwordx2 v[90:91], v[4:5] offset:32
	ds_read_b128 v[4:7], v87 offset:57856
	s_waitcnt lgkmcnt(0)
	v_mfma_f32_16x16x32_f16 v[40:43], v[4:7], v[8:11], 0
	ds_read_b128 v[4:7], v87 offset:57920
	s_waitcnt lgkmcnt(0)
	v_mfma_f32_16x16x32_f16 v[40:43], v[4:7], v[12:15], v[40:43]
	ds_read_b128 v[4:7], v87 offset:57984
	s_waitcnt lgkmcnt(0)
	v_mfma_f32_16x16x32_f16 v[40:43], v[4:7], v[16:19], v[40:43]
	ds_read_b128 v[4:7], v87 offset:58048
	s_waitcnt lgkmcnt(0)
	v_mfma_f32_16x16x32_f16 v[40:43], v[4:7], v[36:39], v[40:43]
	s_nop 7
	v_cvt_pkrtz_f16_f32 v4, v40, v41
	v_cvt_pkrtz_f16_f32 v5, v42, v43
	flat_store_dwordx2 v[90:91], v[4:5] offset:64
	ds_read_b128 v[4:7], v88 offset:57856
	s_waitcnt lgkmcnt(0)
	v_mfma_f32_16x16x32_f16 v[40:43], v[4:7], v[8:11], 0
	ds_read_b128 v[4:7], v88 offset:57920
	s_waitcnt lgkmcnt(0)
	v_mfma_f32_16x16x32_f16 v[8:11], v[4:7], v[12:15], v[40:43]
	ds_read_b128 v[4:7], v88 offset:57984
	v_lshl_add_u64 v[12:13], v[32:33], 1, v[44:45]
	s_waitcnt lgkmcnt(0)
	v_mfma_f32_16x16x32_f16 v[8:11], v[4:7], v[16:19], v[8:11]
	ds_read_b128 v[4:7], v88 offset:58048
	s_waitcnt lgkmcnt(0)
	v_mfma_f32_16x16x32_f16 v[8:11], v[4:7], v[36:39], v[8:11]
	s_nop 7
	v_cvt_pkrtz_f16_f32 v4, v8, v9
	v_cvt_pkrtz_f16_f32 v5, v10, v11
	flat_store_dwordx2 v[12:13], v[4:5]
	s_cbranch_scc0 .LBB0_503
	s_branch .LBB0_589

; #define LAS __attribute__((address_space(3)))
; __device__ __forceinline__ int opaque_tid(int wid_s) { int l = __builtin_amdgcn_mbcnt_hi(~0u, __builtin_amdgcn_mbcnt_lo(~0u, 0u)); asm volatile("" : "+v"(l)); return (wid_s << 6) | l; }
; __device__ __forceinline__ unsigned cvt_pk_bf16(float lo, float hi) { return __builtin_bit_cast(unsigned, __builtin_amdgcn_cvt_pkrtz(lo, hi)); }
; __host__ __device__ __forceinline__ int in_logical_pn(int j) { return (j < 6) ? j : (j < 8 ? j + 2 : j - 2); }
; #define bx (opaque_bx())
; __device__ __forceinline__ void prep_load(const PrepTask& T, f32x4 (&r)[8], int tid) {
;     const int w = tid >> 6, s4 = tid & 63; const int col = colmap(T.kind, T.kind == KIND_IN ? in_logical_pn(T.pn) : T.pn, 4 * s4);
; #pragma unroll
;     for (int i = 0; i < 8; ++i) r[i] = __builtin_nontemporal_load((const f32x4*)(T.src + (size_t)(T.k0 + 8 * w + i) * T.Nnat + col));
; }
; __device__ __forceinline__ void phase_prep(int wid_s, const Args& a, unsigned char* shm) {
;     const int tid = opaque_tid(wid_s), G = gridDim.x, bx = blockIdx.x;
;     float* Ts = (float*)shm;
;     {
;         LAS unsigned* Lp = (LAS unsigned*)shm;
;         f32x4 r[8]; int j = 0; int t = bx * 4; PrepTask T;
;         if (t < PT_TOTAL) { T = prep_decode(a, t); prep_load(T, r, tid); }
;         while (t < PT_TOTAL) {
;             { const int w = tid >> 6, s4 = tid & 63;
; #pragma unroll
;               for (int q = 0; q < 4; ++q) { const u32x4 pc = {cvt_pk_bf16(r[0][q], r[1][q]), cvt_pk_bf16(r[2][q], r[3][q]), cvt_pk_bf16(r[4][q], r[5][q]), cvt_pk_bf16(r[6][q], r[7][q])};
;                   *(LAS u32x4*)(Lp + (4 * s4 + q) * 36 + 4 * w) = pc; } }
.LBB0_808:
	s_waitcnt vmcnt(0)
	s_barrier
	s_cmp_gt_u32 s86, 2
	s_cbranch_scc1 .Ltp_done
	v_readlane_b32 s5, v253, 0
	s_sub_u32 s5, s5, 0x60
	s_cbranch_scc1 .Ltp_done
	s_cmp_gt_u32 s5, 0x9f
	s_cbranch_scc1 .Ltp_done
	s_mov_b64 exec, -1
	s_lshr_b32 s6, s5, 2
	s_and_b32 s5, s5, 3
	s_add_i32 s7, s86, 1
	s_mul_i32 s8, s7, 0x5600000
	s_mul_i32 s9, s5, 0x1580000
	s_add_u32 s8, s8, s9
	s_lshl_b32 s9, s6, 9
	s_add_u32 s8, s8, s9
	v_readlane_b32 s0, v253, 23
	v_readlane_b32 s1, v253, 24
	s_add_u32 s0, s0, s8
	s_addc_u32 s1, s1, 0
	s_mul_i32 s8, s7, 0x2b00000
	s_add_u32 s8, s8, 0x4800000
	s_lshl_b32 s9, s6, 20
	s_add_u32 s8, s8, s9
	s_lshl_b32 s9, s5, 10
	s_add_u32 s8, s8, s9
	s_add_u32 s2, s72, s8
	s_addc_u32 s3, s73, 0
	v_mbcnt_lo_u32_b32 v114, -1, 0
	v_mbcnt_hi_u32_b32 v114, -1, v114
	v_readlane_b32 s5, v253, 37
	s_lshr_b32 s6, s5, 6
	v_bfe_u32 v115, v114, 5, 1
	v_mul_u32_u24_e32 v115, 0x5600, v115
	v_bfe_u32 v116, v114, 3, 2
	v_lshl_add_u32 v115, v116, 7, v115
	v_and_b32_e32 v116, 3, v114
	v_lshl_add_u32 v115, v116, 5, v115
	v_bfe_u32 v116, v114, 2, 1
	v_lshl_add_u32 v115, v116, 4, v115
	s_mul_i32 s7, s6, 0x56000
	v_add_u32_e32 v100, s7, v115
	v_add_u32_e32 v101, 0xac00, v100
	v_add_u32_e32 v102, 0xac00, v101
	v_add_u32_e32 v103, 0xac00, v102
	v_add_u32_e32 v104, 0xac00, v103
	v_add_u32_e32 v105, 0xac00, v104
	v_add_u32_e32 v106, 0xac00, v105
	v_add_u32_e32 v107, 0xac00, v106
	v_mul_u32_u24_e32 v108, 0x240, v114
	s_lshl_b32 s7, s6, 4
	v_add_u32_e32 v108, s7, v108
	v_lshrrev_b32_e32 v116, 3, v114
	s_lshl_b32 s7, s6, 3
	v_add_u32_e32 v116, s7, v116
	v_and_b32_e32 v117, 7, v114
	v_lshlrev_b32_e32 v117, 4, v117
	v_mul_u32_u24_e32 v109, 0x90, v116
	v_add_u32_e32 v109, v109, v117
	v_lshl_add_u32 v110, v116, 12, v117
	v_add_u32_e32 v111, 0x40000, v110
	v_add_u32_e32 v112, 0x40000, v111
	v_add_u32_e32 v113, 0x40000, v112
	global_load_dwordx4 v[4:7], v100, s[0:1] nt
	global_load_dwordx4 v[8:11], v101, s[0:1] nt
	global_load_dwordx4 v[12:15], v102, s[0:1] nt
	global_load_dwordx4 v[16:19], v103, s[0:1] nt
	global_load_dwordx4 v[20:23], v104, s[0:1] nt
	global_load_dwordx4 v[24:27], v105, s[0:1] nt
	global_load_dwordx4 v[28:31], v106, s[0:1] nt
	global_load_dwordx4 v[32:35], v107, s[0:1] nt
	s_add_u32 s0, s0, 0x2b0000
	s_addc_u32 s1, s1, 0
	global_load_dwordx4 v[36:39], v100, s[0:1] nt
	global_load_dwordx4 v[40:43], v101, s[0:1] nt
	global_load_dwordx4 v[44:47], v102, s[0:1] nt
	global_load_dwordx4 v[48:51], v103, s[0:1] nt
	global_load_dwordx4 v[52:55], v104, s[0:1] nt
	global_load_dwordx4 v[56:59], v105, s[0:1] nt
	global_load_dwordx4 v[60:63], v106, s[0:1] nt
	global_load_dwordx4 v[64:67], v107, s[0:1] nt
	s_add_u32 s0, s0, 0x2b0000
	s_addc_u32 s1, s1, 0
	s_mov_b32 s4, 1
	s_waitcnt vmcnt(8)
; #define LAS __attribute__((address_space(3)))
; __device__ __forceinline__ unsigned cvt_pk_bf16(float lo, float hi) { return __builtin_bit_cast(unsigned, __builtin_amdgcn_cvt_pkrtz(lo, hi)); }
; #define bx (opaque_bx())
; __device__ __forceinline__ void phase_prep(int wid_s, const Args& a, unsigned char* shm) {
;     ...
;             { const int w = tid >> 6, s4 = tid & 63;
; #pragma unroll
;               for (int q = 0; q < 4; ++q) { const u32x4 pc = {cvt_pk_bf16(r[0][q], r[1][q]), cvt_pk_bf16(r[2][q], r[3][q]), cvt_pk_bf16(r[4][q], r[5][q]), cvt_pk_bf16(r[6][q], r[7][q])};
;                   *(LAS u32x4*)(Lp + (4 * s4 + q) * 36 + 4 * w) = pc; } }
;             __syncthreads();
;             const PrepTask C = T; ++j; const int tn = ((j >> 2) * G + bx) * 4 + (j & 3);
;             if (tn < PT_TOTAL) { T = prep_decode(a, tn); prep_load(T, r, tid); }
; #pragma unroll
;             for (int q = 0; q < 4; ++q) { const int row = q * 64 + (tid >> 3), pc = tid & 7;
;                 const u32x4 v = *(const LAS u32x4*)(Lp + row * 36 + 4 * pc);
;                 *(u32x4*)(C.dst + (size_t)(256 * C.pn + row) * C.K + C.k0 + 8 * pc) = v; }
;             __syncthreads();
;             t = tn;
.Ltp_loop:
	v_cvt_pkrtz_f16_f32 v68, v4, v8
	v_cvt_pkrtz_f16_f32 v69, v12, v16
	v_cvt_pkrtz_f16_f32 v70, v20, v24
	v_cvt_pkrtz_f16_f32 v71, v28, v32
	ds_write_b128 v108, v[68:71] offset:0
	v_cvt_pkrtz_f16_f32 v72, v5, v9
	v_cvt_pkrtz_f16_f32 v73, v13, v17
	v_cvt_pkrtz_f16_f32 v74, v21, v25
	v_cvt_pkrtz_f16_f32 v75, v29, v33
	ds_write_b128 v108, v[72:75] offset:144
	v_cvt_pkrtz_f16_f32 v76, v6, v10
	v_cvt_pkrtz_f16_f32 v77, v14, v18
	v_cvt_pkrtz_f16_f32 v78, v22, v26
	v_cvt_pkrtz_f16_f32 v79, v30, v34
	ds_write_b128 v108, v[76:79] offset:288
	v_cvt_pkrtz_f16_f32 v80, v7, v11
	v_cvt_pkrtz_f16_f32 v81, v15, v19
	v_cvt_pkrtz_f16_f32 v82, v23, v27
	v_cvt_pkrtz_f16_f32 v83, v31, v35
	ds_write_b128 v108, v[80:83] offset:432
	s_waitcnt lgkmcnt(0)
	s_barrier
	ds_read_b128 v[84:87], v109 offset:0
	ds_read_b128 v[88:91], v109 offset:9216
	ds_read_b128 v[92:95], v109 offset:18432
	ds_read_b128 v[96:99], v109 offset:27648
	s_waitcnt lgkmcnt(3)
	global_store_dwordx4 v110, v[84:87], s[2:3]
	s_waitcnt lgkmcnt(2)
	global_store_dwordx4 v111, v[88:91], s[2:3]
	s_waitcnt lgkmcnt(1)
	global_store_dwordx4 v112, v[92:95], s[2:3]
	s_waitcnt lgkmcnt(0)
	global_store_dwordx4 v113, v[96:99], s[2:3]
	s_add_u32 s2, s2, 0x80
	s_addc_u32 s3, s3, 0
	s_cmp_eq_u32 s4, 0
	s_cbranch_scc1 .Ltp_last
	global_load_dwordx4 v[4:7], v100, s[0:1] nt
	global_load_dwordx4 v[8:11], v101, s[0:1] nt
	global_load_dwordx4 v[12:15], v102, s[0:1] nt
	global_load_dwordx4 v[16:19], v103, s[0:1] nt
	global_load_dwordx4 v[20:23], v104, s[0:1] nt
	global_load_dwordx4 v[24:27], v105, s[0:1] nt
	global_load_dwordx4 v[28:31], v106, s[0:1] nt
	global_load_dwordx4 v[32:35], v107, s[0:1] nt
	s_add_u32 s0, s0, 0x2b0000
	s_addc_u32 s1, s1, 0
	s_waitcnt vmcnt(12)
	v_cvt_pkrtz_f16_f32 v68, v36, v40
	v_cvt_pkrtz_f16_f32 v69, v44, v48
	v_cvt_pkrtz_f16_f32 v70, v52, v56
	v_cvt_pkrtz_f16_f32 v71, v60, v64
	ds_write_b128 v108, v[68:71] offset:36864
	v_cvt_pkrtz_f16_f32 v72, v37, v41
	v_cvt_pkrtz_f16_f32 v73, v45, v49
	v_cvt_pkrtz_f16_f32 v74, v53, v57
	v_cvt_pkrtz_f16_f32 v75, v61, v65
	ds_write_b128 v108, v[72:75] offset:37008
	v_cvt_pkrtz_f16_f32 v76, v38, v42
	v_cvt_pkrtz_f16_f32 v77, v46, v50
	v_cvt_pkrtz_f16_f32 v78, v54, v58
	v_cvt_pkrtz_f16_f32 v79, v62, v66
	ds_write_b128 v108, v[76:79] offset:37152
	v_cvt_pkrtz_f16_f32 v80, v39, v43
	v_cvt_pkrtz_f16_f32 v81, v47, v51
	v_cvt_pkrtz_f16_f32 v82, v55, v59
	v_cvt_pkrtz_f16_f32 v83, v63, v67
	ds_write_b128 v108, v[80:83] offset:37296
	s_waitcnt lgkmcnt(0)
	s_barrier
	ds_read_b128 v[84:87], v109 offset:36864
	ds_read_b128 v[88:91], v109 offset:46080
	ds_read_b128 v[92:95], v109 offset:55296
	ds_read_b128 v[96:99], v109 offset:64512
	s_waitcnt lgkmcnt(3)
	global_store_dwordx4 v110, v[84:87], s[2:3]
	s_waitcnt lgkmcnt(2)
	global_store_dwordx4 v111, v[88:91], s[2:3]
	s_waitcnt lgkmcnt(1)
	global_store_dwordx4 v112, v[92:95], s[2:3]
	s_waitcnt lgkmcnt(0)
	global_store_dwordx4 v113, v[96:99], s[2:3]
	s_add_u32 s2, s2, 0x80
	s_addc_u32 s3, s3, 0
	global_load_dwordx4 v[36:39], v100, s[0:1] nt
	global_load_dwordx4 v[40:43], v101, s[0:1] nt
	global_load_dwordx4 v[44:47], v102, s[0:1] nt
	global_load_dwordx4 v[48:51], v103, s[0:1] nt
	global_load_dwordx4 v[52:55], v104, s[0:1] nt
	global_load_dwordx4 v[56:59], v105, s[0:1] nt
	global_load_dwordx4 v[60:63], v106, s[0:1] nt
	global_load_dwordx4 v[64:67], v107, s[0:1] nt
	s_add_u32 s0, s0, 0x2b0000
	s_addc_u32 s1, s1, 0
	s_sub_u32 s4, s4, 1
	s_waitcnt vmcnt(12)
	s_branch .Ltp_loop
.Ltp_last:
	s_waitcnt vmcnt(4)
	v_cvt_pkrtz_f16_f32 v68, v36, v40
	v_cvt_pkrtz_f16_f32 v69, v44, v48
	v_cvt_pkrtz_f16_f32 v70, v52, v56
	v_cvt_pkrtz_f16_f32 v71, v60, v64
	ds_write_b128 v108, v[68:71] offset:36864
	v_cvt_pkrtz_f16_f32 v72, v37, v41
	v_cvt_pkrtz_f16_f32 v73, v45, v49
	v_cvt_pkrtz_f16_f32 v74, v53, v57
	v_cvt_pkrtz_f16_f32 v75, v61, v65
	ds_write_b128 v108, v[72:75] offset:37008
	v_cvt_pkrtz_f16_f32 v76, v38, v42
	v_cvt_pkrtz_f16_f32 v77, v46, v50
	v_cvt_pkrtz_f16_f32 v78, v54, v58
	v_cvt_pkrtz_f16_f32 v79, v62, v66
	ds_write_b128 v108, v[76:79] offset:37152
	v_cvt_pkrtz_f16_f32 v80, v39, v43
	v_cvt_pkrtz_f16_f32 v81, v47, v51
	v_cvt_pkrtz_f16_f32 v82, v55, v59
	v_cvt_pkrtz_f16_f32 v83, v63, v67
	ds_write_b128 v108, v[80:83] offset:37296
	s_waitcnt lgkmcnt(0)
	s_barrier
	ds_read_b128 v[84:87], v109 offset:36864
	ds_read_b128 v[88:91], v109 offset:46080
	ds_read_b128 v[92:95], v109 offset:55296
	ds_read_b128 v[96:99], v109 offset:64512
	s_waitcnt lgkmcnt(3)
	global_store_dwordx4 v110, v[84:87], s[2:3]
	s_waitcnt lgkmcnt(2)
	global_store_dwordx4 v111, v[88:91], s[2:3]
	s_waitcnt lgkmcnt(1)
	global_store_dwordx4 v112, v[92:95], s[2:3]
	s_waitcnt lgkmcnt(0)
	global_store_dwordx4 v113, v[96:99], s[2:3]
	s_add_u32 s2, s2, 0x80
	s_addc_u32 s3, s3, 0
.Ltp_done:
.LBB0_809:
	s_or_b32 s10, s81, 7
	s_cmp_ge_i32 s10, s75
	s_waitcnt lgkmcnt(0)
	s_barrier
	s_cbranch_scc1 .LBB0_855
	s_waitcnt vmcnt(0)
	v_mov_b32_e32 v0, v240
	v_readlane_b32 s0, v253, 38
	s_barrier
	v_readlane_b32 s1, v253, 39
	v_cmp_eq_u32_e32 vcc, 0, v0
	s_and_b64 s[0:1], s[0:1], vcc
	s_and_saveexec_b64 s[36:37], s[0:1]
	s_cbranch_execz .LBB0_854
	v_readlane_b32 s38, v253, 2
	v_readlane_b32 s1, v253, 47
	v_readlane_b32 s39, v253, 3
	s_getreg_b32 s0, hwreg(HW_REG_XCC_ID, 0, 4)
	v_mov_b32_e32 v0, s1
	s_waitcnt vmcnt(0) expcnt(0) lgkmcnt(0)
	ds_read_b32 v4, v0
	v_readlane_b32 s1, v253, 48
	s_and_b32 s40, s0, 15
	s_waitcnt lgkmcnt(0)
	v_cmp_ne_u32_e32 vcc, 0, v4
	v_mov_b32_e32 v0, s1
	ds_read_b32 v0, v0
	s_cbranch_vccnz .LBB0_825
	s_add_u32 s0, s38, 0x1000
	s_addc_u32 s1, s39, 0
	s_add_u32 s2, s38, 0x1100
	s_addc_u32 s3, s39, 0
	s_add_u32 s4, s38, 0x1200
	s_addc_u32 s5, s39, 0
	s_add_u32 s6, s38, 0x1300
	s_addc_u32 s7, s39, 0
	s_mov_b32 s30, 1
	s_mov_b64 s[8:9], 0
	s_branch .LBB0_815

; __global__ void __launch_bounds__(NTHREADS, 2) fwd_kernel(Args a) {
	.amdhsa_kernel _Z10fwd_kernel4Args
		.amdhsa_group_segment_fixed_size 0
		.amdhsa_private_segment_fixed_size 0
		.amdhsa_kernarg_size 464
		.amdhsa_user_sgpr_count 2
		.amdhsa_user_sgpr_dispatch_ptr 0
		.amdhsa_user_sgpr_queue_ptr 0
		.amdhsa_user_sgpr_kernarg_segment_ptr 1
		.amdhsa_user_sgpr_dispatch_id 0
		.amdhsa_user_sgpr_kernarg_preload_length 0
		.amdhsa_user_sgpr_kernarg_preload_offset 0
		.amdhsa_user_sgpr_private_segment_size 0
		.amdhsa_uses_dynamic_stack 0
		.amdhsa_enable_private_segment 0
		.amdhsa_system_sgpr_workgroup_id_x 1
		.amdhsa_system_sgpr_workgroup_id_y 0
		.amdhsa_system_sgpr_workgroup_id_z 0
		.amdhsa_system_sgpr_workgroup_info 0
		.amdhsa_system_vgpr_workitem_id 2
		.amdhsa_next_free_vgpr 256
		.amdhsa_next_free_sgpr 100
		.amdhsa_accum_offset 256
		.amdhsa_reserve_vcc 1
		.amdhsa_float_round_mode_32 0
		.amdhsa_float_round_mode_16_64 0
		.amdhsa_float_denorm_mode_32 3
		.amdhsa_float_denorm_mode_16_64 3
		.amdhsa_dx10_clamp 1
		.amdhsa_ieee_mode 1
		.amdhsa_fp16_overflow 0
		.amdhsa_tg_split 0
		.amdhsa_exception_fp_ieee_invalid_op 0
		.amdhsa_exception_fp_denorm_src 0
		.amdhsa_exception_fp_ieee_div_zero 0
		.amdhsa_exception_fp_ieee_overflow 0
		.amdhsa_exception_fp_ieee_underflow 0
		.amdhsa_exception_fp_ieee_inexact 0
		.amdhsa_exception_int_div_zero 0
	.end_amdhsa_kernel

amdhsa.kernels:
  - .agpr_count:     0
    .args:
      - .offset:         0
        .size:           208
        .value_kind:     by_value
      - .offset:         208
        .size:           4
        .value_kind:     hidden_block_count_x
      - .offset:         212
        .size:           4
        .value_kind:     hidden_block_count_y
      - .offset:         216
        .size:           4
        .value_kind:     hidden_block_count_z
      - .offset:         220
        .size:           2
        .value_kind:     hidden_group_size_x
      - .offset:         222
        .size:           2
        .value_kind:     hidden_group_size_y
      - .offset:         224
        .size:           2
        .value_kind:     hidden_group_size_z
      - .offset:         226
        .size:           2
        .value_kind:     hidden_remainder_x
      - .offset:         228
        .size:           2
        .value_kind:     hidden_remainder_y
      - .offset:         230
        .size:           2
        .value_kind:     hidden_remainder_z
      - .offset:         248
        .size:           8
        .value_kind:     hidden_global_offset_x
      - .offset:         256
        .size:           8
        .value_kind:     hidden_global_offset_y
      - .offset:         264
        .size:           8
        .value_kind:     hidden_global_offset_z
      - .offset:         272
        .size:           2
        .value_kind:     hidden_grid_dims
      - .offset:         296
        .size:           8
        .value_kind:     hidden_multigrid_sync_arg
      - .offset:         328
        .size:           4
        .value_kind:     hidden_dynamic_lds_size
    .group_segment_fixed_size: 0
    .kernarg_segment_align: 8
    .kernarg_segment_size: 464
    .language:       OpenCL C
    .language_version:
      - 2
      - 0
    .max_flat_workgroup_size: 512
    .name:           _Z10fwd_kernel4Args
    .private_segment_fixed_size: 0
    .sgpr_count:     106
    .sgpr_spill_count: 169
    .symbol:         _Z10fwd_kernel4Args.kd
    .uniform_work_group_size: 1
    .uses_dynamic_stack: false
    .vgpr_count:     256
    .vgpr_spill_count: 0
    .wavefront_size: 64
